# G6 (MLP down-proj) retiled 256x256 -> 192x256 so all 256 CUs get one tile (was 192 of 256); per-32-row gate select in residual epilogue
# speedup vs baseline: 1.0102x; 1.0102x over previous
.LBB0_219:
	s_mov_b64 s[74:75], 0
	s_add_u32 s66, s56, s74
	v_readlane_b32 s4, v250, 1
	s_addc_u32 s67, s57, s75
	s_lshl_b64 s[30:31], s[74:75], 2
	v_readlane_b32 s6, v250, 3
	v_readlane_b32 s7, v250, 4
	s_add_u32 s68, s6, s30
	s_addc_u32 s69, s7, s31
	s_cmp_lt_i32 s72, 6
	s_mov_b64 s[0:1], -1
	v_readlane_b32 s27, v254, 28
	v_readlane_b32 s5, v250, 2
	s_cbranch_scc1 .LBB0_794
	s_cmp_lt_i32 s72, 8
	s_cbranch_scc1 .LBB0_256
	s_cmp_gt_i32 s72, 8
	s_cbranch_scc0 .LBB0_238
	s_mov_b64 s[0:1], src_shared_base
	s_add_i32 s0, 0, 0x2100c
	s_cmp_lg_u32 s0, -1
	s_cselect_b32 s0, s0, 0
	s_cselect_b32 s4, s1, 0
	v_mov_b32_e32 v2, s0
	s_add_i32 s0, 0, 0x21008
	s_cmp_lg_u32 s0, -1
	v_mov_b32_e32 v0, v224
	v_mov_b32_e32 v3, s4
	s_cselect_b32 s0, s0, 0
	s_cselect_b32 s1, s1, 0
	flat_load_dword v1, v[2:3] sc0 sc1
	s_waitcnt vmcnt(0)
	v_mov_b32_e32 v2, s0
	v_mov_b32_e32 v3, s1
	flat_load_dword v147, v[2:3] sc0 sc1
	s_waitcnt vmcnt(0) lgkmcnt(0)
	v_cmp_gt_i32_e32 vcc, 32, v147
	s_and_saveexec_b64 s[36:37], vcc
	s_cbranch_execz .LBB0_237
	v_lshlrev_b32_e32 v166, 3, v1
	v_ashrrev_i32_e32 v1, 31, v147
	v_lshrrev_b32_e32 v1, 30, v1
	v_add_u32_e32 v1, v147, v1
	v_lshrrev_b32_e32 v2, 2, v1
	v_and_b32_e32 v1, 0xfffffc, v1
	v_sub_u32_e32 v1, v147, v1
	v_lshlrev_b32_e32 v148, 8, v1
	v_lshrrev_b32_e32 v1, 4, v0
	v_xor_b32_e32 v1, v1, v0
	s_add_u32 s38, s66, 0x4553700
	v_lshlrev_b32_e32 v1, 4, v1
	s_addc_u32 s39, s67, 0
	s_lshl_b32 s0, s23, 1
	v_add_u32_e32 v146, v2, v166
	v_mul_u32_u24_e32 v146, 0xc0, v146
	v_and_b32_e32 v128, 0x70, v1
	v_ashrrev_i32_e32 v1, 3, v0
	s_add_u32 s0, s66, s0
	v_add_u32_e32 v4, v146, v1
	s_addc_u32 s1, s67, 0
	v_ashrrev_i32_e32 v5, 31, v4
	v_lshl_add_u32 v6, v0, 4, 0
	s_add_u32 s40, s0, 0x1c4b700
	v_lshl_add_u64 v[2:3], s[38:39], 0, v[128:129]
	v_lshlrev_b64 v[4:5], 13, v[4:5]
	v_readfirstlane_b32 s0, v6
	v_add_u32_e32 v7, 0x200, v0
	v_lshl_add_u64 v[4:5], v[2:3], 0, v[4:5]
	s_mov_b32 m0, s0
	v_ashrrev_i32_e32 v8, 3, v7
	global_load_lds_dwordx4 v[4:5], off
	v_add_u32_e32 v4, v146, v8
	v_ashrrev_i32_e32 v5, 31, v4
	v_lshl_add_u32 v7, v7, 4, 0
	v_lshlrev_b64 v[4:5], 13, v[4:5]
	v_readfirstlane_b32 s0, v7
	v_add_u32_e32 v9, 0x400, v0
	v_lshl_add_u64 v[4:5], v[2:3], 0, v[4:5]
	s_mov_b32 m0, s0
	v_ashrrev_i32_e32 v10, 3, v9
	global_load_lds_dwordx4 v[4:5], off
	v_add_u32_e32 v4, v146, v10
	v_ashrrev_i32_e32 v5, 31, v4
	v_lshl_add_u32 v9, v9, 4, 0
	v_lshlrev_b64 v[4:5], 13, v[4:5]
	v_readfirstlane_b32 s0, v9
	v_add_u32_e32 v11, 0x600, v0
	v_lshl_add_u64 v[4:5], v[2:3], 0, v[4:5]
	s_mov_b32 m0, s0
	v_ashrrev_i32_e32 v12, 3, v11
	global_load_lds_dwordx4 v[4:5], off
	v_add_u32_e32 v4, v146, v12
	v_ashrrev_i32_e32 v5, 31, v4
	v_lshlrev_b64 v[4:5], 13, v[4:5]
	v_lshl_add_u32 v11, v11, 4, 0
	v_lshl_add_u64 v[2:3], v[2:3], 0, v[4:5]
	v_readfirstlane_b32 s0, v11
	v_add_u32_e32 v4, v148, v1
	s_addc_u32 s41, s1, 0
	s_mov_b32 m0, s0
	v_ashrrev_i32_e32 v5, 31, v4
	v_add_u32_e32 v1, 0x8000, v6
	v_lshl_add_u64 v[2:3], s[40:41], 0, v[128:129]
	v_lshlrev_b64 v[4:5], 13, v[4:5]
	v_readfirstlane_b32 s0, v1
	v_lshl_add_u64 v[4:5], v[2:3], 0, v[4:5]
	s_mov_b32 m0, s0
	v_add_u32_e32 v1, 0x8000, v7
	global_load_lds_dwordx4 v[4:5], off
	v_add_u32_e32 v4, v148, v8
	v_ashrrev_i32_e32 v5, 31, v4
	v_lshlrev_b64 v[4:5], 13, v[4:5]
	v_readfirstlane_b32 s0, v1
	v_lshl_add_u64 v[4:5], v[2:3], 0, v[4:5]
	s_mov_b32 m0, s0
	v_add_u32_e32 v1, 0x8000, v9
	global_load_lds_dwordx4 v[4:5], off
	v_add_u32_e32 v4, v148, v10
	v_ashrrev_i32_e32 v5, 31, v4
	v_lshlrev_b64 v[4:5], 13, v[4:5]
	v_readfirstlane_b32 s0, v1
	v_lshl_add_u64 v[4:5], v[2:3], 0, v[4:5]
	s_mov_b32 m0, s0
	v_add_u32_e32 v1, 0x8000, v11
	global_load_lds_dwordx4 v[4:5], off
	v_add_u32_e32 v4, v148, v12
	v_ashrrev_i32_e32 v5, 31, v4
	v_lshlrev_b64 v[4:5], 13, v[4:5]
	v_readfirstlane_b32 s0, v1
	v_lshl_add_u64 v[2:3], v[2:3], 0, v[4:5]
	s_mov_b32 m0, s0
	s_load_dword s0, s[24:25], 0x0
	global_load_lds_dwordx4 v[2:3], off
	v_ashrrev_i32_e32 v1, 1, v0
	v_and_b32_e32 v167, 0xdf, v0
	v_lshrrev_b32_e32 v0, 3, v0
	s_waitcnt lgkmcnt(0)
	s_lshr_b32 s8, s0, 3
	v_and_b32_e32 v0, 4, v0
	s_movk_i32 s0, 0xff80
	v_lshrrev_b32_e32 v1, 8, v224
	v_mul_u32_u24_e32 v1, 0x60, v1
	v_add_u32_e32 v168, v1, v0
	v_readlane_b32 s0, v253, 57
	s_add_u32 s42, s0, s74
	v_readlane_b32 s0, v253, 58
	s_addc_u32 s43, s0, s75
	v_readlane_b32 s0, v254, 59
	s_add_u32 s44, s0, s74
	v_readlane_b32 s0, v254, 60
	s_addc_u32 s45, s0, s75
	s_mov_b32 s9, 0
	s_mov_b64 s[46:47], 0
	s_branch .LBB0_225
.LBB0_224:
	s_or_b64 exec, exec, s[0:1]
	v_add_u32_e32 v222, v170, v168
	v_or_b32_e32 v223, v169, v167
	v_lshlrev_b32_e32 v221, 12, v222
	v_lshl_add_u32 v221, v223, 2, v221
	s_mov_b32 s0, s68
	s_mov_b32 s1, s69
	global_load_dword v189, v221, s[0:1]
	global_load_dword v205, v221, s[0:1] offset:128
	s_add_u32 s0, s68, 0x1000
	s_addc_u32 s1, s69, 0
	global_load_dword v190, v221, s[0:1]
	global_load_dword v206, v221, s[0:1] offset:128
	s_add_u32 s0, s68, 0x2000
	s_addc_u32 s1, s69, 0
	global_load_dword v191, v221, s[0:1]
	global_load_dword v207, v221, s[0:1] offset:128
	s_add_u32 s0, s68, 0x3000
	s_addc_u32 s1, s69, 0
	global_load_dword v192, v221, s[0:1]
	global_load_dword v208, v221, s[0:1] offset:128
	s_add_u32 s0, s68, 0x8000
	s_addc_u32 s1, s69, 0
	global_load_dword v193, v221, s[0:1]
	global_load_dword v209, v221, s[0:1] offset:128
	s_add_u32 s0, s68, 0x9000
	s_addc_u32 s1, s69, 0
	global_load_dword v194, v221, s[0:1]
	global_load_dword v210, v221, s[0:1] offset:128
	s_add_u32 s0, s68, 0xa000
	s_addc_u32 s1, s69, 0
	global_load_dword v195, v221, s[0:1]
	global_load_dword v211, v221, s[0:1] offset:128
	s_add_u32 s0, s68, 0xb000
	s_addc_u32 s1, s69, 0
	global_load_dword v196, v221, s[0:1]
	global_load_dword v212, v221, s[0:1] offset:128
	s_add_u32 s0, s68, 0x10000
	s_addc_u32 s1, s69, 0
	global_load_dword v197, v221, s[0:1]
	global_load_dword v213, v221, s[0:1] offset:128
	s_add_u32 s0, s68, 0x11000
	s_addc_u32 s1, s69, 0
	global_load_dword v198, v221, s[0:1]
	global_load_dword v214, v221, s[0:1] offset:128
	s_add_u32 s0, s68, 0x12000
	s_addc_u32 s1, s69, 0
	global_load_dword v199, v221, s[0:1]
	global_load_dword v215, v221, s[0:1] offset:128
	s_add_u32 s0, s68, 0x13000
	s_addc_u32 s1, s69, 0
	global_load_dword v200, v221, s[0:1]
	global_load_dword v216, v221, s[0:1] offset:128
	s_add_u32 s0, s68, 0x18000
	s_addc_u32 s1, s69, 0
	global_load_dword v201, v221, s[0:1]
	global_load_dword v217, v221, s[0:1] offset:128
	s_add_u32 s0, s68, 0x19000
	s_addc_u32 s1, s69, 0
	global_load_dword v202, v221, s[0:1]
	global_load_dword v218, v221, s[0:1] offset:128
	s_add_u32 s0, s68, 0x1a000
	s_addc_u32 s1, s69, 0
	global_load_dword v203, v221, s[0:1]
	global_load_dword v219, v221, s[0:1] offset:128
	s_add_u32 s0, s68, 0x1b000
	s_addc_u32 s1, s69, 0
	global_load_dword v204, v221, s[0:1]
	global_load_dword v220, v221, s[0:1] offset:128
	v_add_u32_e32 v131, v130, v172
	ds_read_b128 v[132:135], v131
	ds_read_b128 v[136:139], v131 offset:4096
	ds_read_b128 v[140:143], v131 offset:8192
	v_add_u32_e32 v131, v128, v172
	ds_read_b128 v[154:157], v131 offset:32768
	ds_read_b128 v[158:161], v131 offset:36864
	s_setprio 1
	s_waitcnt lgkmcnt(0)
	v_mfma_f32_32x32x16_bf16 v[112:127], v[132:135], v[154:157], v[112:127]
	v_mfma_f32_32x32x16_bf16 v[96:111], v[132:135], v[158:161], v[96:111]
	v_mfma_f32_32x32x16_bf16 v[80:95], v[136:139], v[154:157], v[80:95]
	v_mfma_f32_32x32x16_bf16 v[64:79], v[136:139], v[158:161], v[64:79]
	v_mfma_f32_32x32x16_bf16 v[48:63], v[140:143], v[154:157], v[48:63]
	v_mfma_f32_32x32x16_bf16 v[32:47], v[140:143], v[158:161], v[32:47]
	s_setprio 0
	v_add_u32_e32 v142, v130, v171
	ds_read_b128 v[130:133], v142
	ds_read_b128 v[134:137], v142 offset:4096
	ds_read_b128 v[138:141], v142 offset:8192
	v_add_u32_e32 v128, v128, v171
	ds_read_b128 v[150:153], v128 offset:32768
	ds_read_b128 v[154:157], v128 offset:36864
	s_setprio 1
	s_waitcnt lgkmcnt(0)
	v_mfma_f32_32x32x16_bf16 v[112:127], v[130:133], v[150:153], v[112:127]
	v_mfma_f32_32x32x16_bf16 v[96:111], v[130:133], v[154:157], v[96:111]
	v_mfma_f32_32x32x16_bf16 v[80:95], v[134:137], v[150:153], v[80:95]
	v_mfma_f32_32x32x16_bf16 v[64:79], v[134:137], v[154:157], v[64:79]
	v_mfma_f32_32x32x16_bf16 v[48:63], v[138:141], v[150:153], v[48:63]
	v_mfma_f32_32x32x16_bf16 v[32:47], v[138:141], v[154:157], v[32:47]
	s_setprio 0
	v_or_b32_e32 v134, v169, v167
	v_readlane_b32 s1, v254, 62
	s_movk_i32 s0, 0x6000
	v_lshlrev_b32_e32 v134, 2, v134
	v_add_u32_e32 v222, v170, v168
	v_add_u32_e32 v134, 0x5000, v134
	v_mov_b32_e32 v135, 0
	v_add_u32_e32 v132, 0xffffe000, v222
	v_ashrrev_i32_e32 v132, 10, v132
	v_add_u32_e32 v132, 1, v132
	v_max_i32_e32 v132, 0, v132
	v_add_u32_e32 v132, s1, v132
	v_mov_b64_e32 v[130:131], s[66:67]
	v_mad_u64_u32 v[130:131], vcc, v132, s0, v[130:131]
	v_lshl_add_u64 v[130:131], v[130:131], 0, v[134:135]
	global_load_dword v128, v[130:131], off
	global_load_dword v133, v[130:131], off offset:128
	v_add_u32_e32 v132, 0xffffe020, v222
	v_ashrrev_i32_e32 v132, 10, v132
	v_add_u32_e32 v132, 1, v132
	v_max_i32_e32 v132, 0, v132
	v_add_u32_e32 v132, s1, v132
	v_mov_b64_e32 v[130:131], s[66:67]
	v_mad_u64_u32 v[130:131], vcc, v132, s0, v[130:131]
	v_lshl_add_u64 v[130:131], v[130:131], 0, v[134:135]
	global_load_dword v142, v[130:131], off
	global_load_dword v143, v[130:131], off offset:128
	v_add_u32_e32 v132, 0xffffe040, v222
	v_ashrrev_i32_e32 v132, 10, v132
	v_add_u32_e32 v132, 1, v132
	v_max_i32_e32 v132, 0, v132
	v_add_u32_e32 v132, s1, v132
	v_mov_b64_e32 v[130:131], s[66:67]
	v_mad_u64_u32 v[130:131], vcc, v132, s0, v[130:131]
	v_lshl_add_u64 v[130:131], v[130:131], 0, v[134:135]
	global_load_dword v144, v[130:131], off
	global_load_dword v145, v[130:131], off offset:128
	s_add_u32 s0, s68, 0x20000
	s_addc_u32 s1, s69, 0
	global_load_dword v150, v221, s[0:1]
	global_load_dword v172, v221, s[0:1] offset:128
	s_add_u32 s0, s68, 0x21000
	s_addc_u32 s1, s69, 0
	global_load_dword v151, v221, s[0:1]
	global_load_dword v173, v221, s[0:1] offset:128
	s_add_u32 s0, s68, 0x22000
	s_addc_u32 s1, s69, 0
	global_load_dword v152, v221, s[0:1]
	global_load_dword v174, v221, s[0:1] offset:128
	s_add_u32 s0, s68, 0x23000
	s_addc_u32 s1, s69, 0
	global_load_dword v153, v221, s[0:1]
	global_load_dword v175, v221, s[0:1] offset:128
	s_add_u32 s0, s68, 0x28000
	s_addc_u32 s1, s69, 0
	global_load_dword v154, v221, s[0:1]
	global_load_dword v176, v221, s[0:1] offset:128
	s_add_u32 s0, s68, 0x29000
	s_addc_u32 s1, s69, 0
	global_load_dword v155, v221, s[0:1]
	global_load_dword v177, v221, s[0:1] offset:128
	s_add_u32 s0, s68, 0x2a000
	s_addc_u32 s1, s69, 0
	global_load_dword v156, v221, s[0:1]
	global_load_dword v178, v221, s[0:1] offset:128
	s_add_u32 s0, s68, 0x2b000
	s_addc_u32 s1, s69, 0
	global_load_dword v157, v221, s[0:1]
	global_load_dword v179, v221, s[0:1] offset:128
	s_add_u32 s0, s68, 0x30000
	s_addc_u32 s1, s69, 0
	global_load_dword v158, v221, s[0:1]
	global_load_dword v180, v221, s[0:1] offset:128
	s_add_u32 s0, s68, 0x31000
	s_addc_u32 s1, s69, 0
	global_load_dword v159, v221, s[0:1]
	global_load_dword v181, v221, s[0:1] offset:128
	s_add_u32 s0, s68, 0x32000
	s_addc_u32 s1, s69, 0
	global_load_dword v160, v221, s[0:1]
	global_load_dword v182, v221, s[0:1] offset:128
	s_add_u32 s0, s68, 0x33000
	s_addc_u32 s1, s69, 0
	global_load_dword v161, v221, s[0:1]
	global_load_dword v183, v221, s[0:1] offset:128
	s_add_u32 s0, s68, 0x38000
	s_addc_u32 s1, s69, 0
	global_load_dword v162, v221, s[0:1]
	global_load_dword v184, v221, s[0:1] offset:128
	s_add_u32 s0, s68, 0x39000
	s_addc_u32 s1, s69, 0
	global_load_dword v163, v221, s[0:1]
	global_load_dword v185, v221, s[0:1] offset:128
	s_add_u32 s0, s68, 0x3a000
	s_addc_u32 s1, s69, 0
	global_load_dword v164, v221, s[0:1]
	global_load_dword v186, v221, s[0:1] offset:128
	s_add_u32 s0, s68, 0x3b000
	s_addc_u32 s1, s69, 0
	global_load_dword v165, v221, s[0:1]
	global_load_dword v187, v221, s[0:1] offset:128
	s_waitcnt vmcnt(32)
	v_fmac_f32_e32 v189, v112, v128
	v_fmac_f32_e32 v190, v113, v128
	v_fmac_f32_e32 v191, v114, v128
	v_fmac_f32_e32 v192, v115, v128
	v_fmac_f32_e32 v193, v116, v128
	v_fmac_f32_e32 v194, v117, v128
	v_fmac_f32_e32 v195, v118, v128
	v_fmac_f32_e32 v196, v119, v128
	v_fmac_f32_e32 v197, v120, v128
	v_fmac_f32_e32 v198, v121, v128
	v_fmac_f32_e32 v199, v122, v128
	v_fmac_f32_e32 v200, v123, v128
	v_fmac_f32_e32 v201, v124, v128
	v_fmac_f32_e32 v202, v125, v128
	v_fmac_f32_e32 v203, v126, v128
	v_fmac_f32_e32 v204, v127, v128
	v_fmac_f32_e32 v205, v96, v133
	v_fmac_f32_e32 v206, v97, v133
	v_fmac_f32_e32 v207, v98, v133
	v_fmac_f32_e32 v208, v99, v133
	v_fmac_f32_e32 v209, v100, v133
	v_fmac_f32_e32 v210, v101, v133
	v_fmac_f32_e32 v211, v102, v133
	v_fmac_f32_e32 v212, v103, v133
	v_fmac_f32_e32 v213, v104, v133
	v_fmac_f32_e32 v214, v105, v133
	v_fmac_f32_e32 v215, v106, v133
	v_fmac_f32_e32 v216, v107, v133
	v_fmac_f32_e32 v217, v108, v133
	v_fmac_f32_e32 v218, v109, v133
	v_fmac_f32_e32 v219, v110, v133
	v_fmac_f32_e32 v220, v111, v133
	s_add_u32 s0, s68, 0x40000
	s_addc_u32 s1, s69, 0
	global_load_dword v0, v221, s[0:1]
	global_load_dword v16, v221, s[0:1] offset:128
	s_add_u32 s0, s68, 0x41000
	s_addc_u32 s1, s69, 0
	global_load_dword v1, v221, s[0:1]
	global_load_dword v17, v221, s[0:1] offset:128
	s_add_u32 s0, s68, 0x42000
	s_addc_u32 s1, s69, 0
	global_load_dword v2, v221, s[0:1]
	global_load_dword v18, v221, s[0:1] offset:128
	s_add_u32 s0, s68, 0x43000
	s_addc_u32 s1, s69, 0
	global_load_dword v3, v221, s[0:1]
	global_load_dword v19, v221, s[0:1] offset:128
	s_add_u32 s0, s68, 0x48000
	s_addc_u32 s1, s69, 0
	global_load_dword v4, v221, s[0:1]
	global_load_dword v20, v221, s[0:1] offset:128
	s_add_u32 s0, s68, 0x49000
	s_addc_u32 s1, s69, 0
	global_load_dword v5, v221, s[0:1]
	global_load_dword v21, v221, s[0:1] offset:128
	s_add_u32 s0, s68, 0x4a000
	s_addc_u32 s1, s69, 0
	global_load_dword v6, v221, s[0:1]
	global_load_dword v22, v221, s[0:1] offset:128
	s_add_u32 s0, s68, 0x4b000
	s_addc_u32 s1, s69, 0
	global_load_dword v7, v221, s[0:1]
	global_load_dword v23, v221, s[0:1] offset:128
	s_add_u32 s0, s68, 0x50000
	s_addc_u32 s1, s69, 0
	global_load_dword v8, v221, s[0:1]
	global_load_dword v24, v221, s[0:1] offset:128
	s_add_u32 s0, s68, 0x51000
	s_addc_u32 s1, s69, 0
	global_load_dword v9, v221, s[0:1]
	global_load_dword v25, v221, s[0:1] offset:128
	s_add_u32 s0, s68, 0x52000
	s_addc_u32 s1, s69, 0
	global_load_dword v10, v221, s[0:1]
	global_load_dword v26, v221, s[0:1] offset:128
	s_add_u32 s0, s68, 0x53000
	s_addc_u32 s1, s69, 0
	global_load_dword v11, v221, s[0:1]
	global_load_dword v27, v221, s[0:1] offset:128
	s_add_u32 s0, s68, 0x58000
	s_addc_u32 s1, s69, 0
	global_load_dword v12, v221, s[0:1]
	global_load_dword v28, v221, s[0:1] offset:128
	s_add_u32 s0, s68, 0x59000
	s_addc_u32 s1, s69, 0
	global_load_dword v13, v221, s[0:1]
	global_load_dword v29, v221, s[0:1] offset:128
	s_add_u32 s0, s68, 0x5a000
	s_addc_u32 s1, s69, 0
	global_load_dword v14, v221, s[0:1]
	global_load_dword v30, v221, s[0:1] offset:128
	s_add_u32 s0, s68, 0x5b000
	s_addc_u32 s1, s69, 0
	global_load_dword v15, v221, s[0:1]
	global_load_dword v31, v221, s[0:1] offset:128
	s_waitcnt vmcnt(32)
	v_fmac_f32_e32 v150, v80, v142
	v_fmac_f32_e32 v151, v81, v142
	v_fmac_f32_e32 v152, v82, v142
	v_fmac_f32_e32 v153, v83, v142
	v_fmac_f32_e32 v154, v84, v142
	v_fmac_f32_e32 v155, v85, v142
	v_fmac_f32_e32 v156, v86, v142
	v_fmac_f32_e32 v157, v87, v142
	v_fmac_f32_e32 v158, v88, v142
	v_fmac_f32_e32 v159, v89, v142
	v_fmac_f32_e32 v160, v90, v142
	v_fmac_f32_e32 v161, v91, v142
	v_fmac_f32_e32 v162, v92, v142
	v_fmac_f32_e32 v163, v93, v142
	v_fmac_f32_e32 v164, v94, v142
	v_fmac_f32_e32 v165, v95, v142
	v_fmac_f32_e32 v172, v64, v143
	v_fmac_f32_e32 v173, v65, v143
	v_fmac_f32_e32 v174, v66, v143
	v_fmac_f32_e32 v175, v67, v143
	v_fmac_f32_e32 v176, v68, v143
	v_fmac_f32_e32 v177, v69, v143
	v_fmac_f32_e32 v178, v70, v143
	v_fmac_f32_e32 v179, v71, v143
	v_fmac_f32_e32 v180, v72, v143
	v_fmac_f32_e32 v181, v73, v143
	v_fmac_f32_e32 v182, v74, v143
	v_fmac_f32_e32 v183, v75, v143
	v_fmac_f32_e32 v184, v76, v143
	v_fmac_f32_e32 v185, v77, v143
	v_fmac_f32_e32 v186, v78, v143
	v_fmac_f32_e32 v187, v79, v143
	s_waitcnt vmcnt(0)
	v_fmac_f32_e32 v0, v48, v144
	v_fmac_f32_e32 v1, v49, v144
	v_fmac_f32_e32 v2, v50, v144
	v_fmac_f32_e32 v3, v51, v144
	v_fmac_f32_e32 v4, v52, v144
	v_fmac_f32_e32 v5, v53, v144
	v_fmac_f32_e32 v6, v54, v144
	v_fmac_f32_e32 v7, v55, v144
	v_fmac_f32_e32 v8, v56, v144
	v_fmac_f32_e32 v9, v57, v144
	v_fmac_f32_e32 v10, v58, v144
	v_fmac_f32_e32 v11, v59, v144
	v_fmac_f32_e32 v12, v60, v144
	v_fmac_f32_e32 v13, v61, v144
	v_fmac_f32_e32 v14, v62, v144
	v_fmac_f32_e32 v15, v63, v144
	v_fmac_f32_e32 v16, v32, v145
	v_fmac_f32_e32 v17, v33, v145
	v_fmac_f32_e32 v18, v34, v145
	v_fmac_f32_e32 v19, v35, v145
	v_fmac_f32_e32 v20, v36, v145
	v_fmac_f32_e32 v21, v37, v145
	v_fmac_f32_e32 v22, v38, v145
	v_fmac_f32_e32 v23, v39, v145
	v_fmac_f32_e32 v24, v40, v145
	v_fmac_f32_e32 v25, v41, v145
	v_fmac_f32_e32 v26, v42, v145
	v_fmac_f32_e32 v27, v43, v145
	v_fmac_f32_e32 v28, v44, v145
	v_fmac_f32_e32 v29, v45, v145
	v_fmac_f32_e32 v30, v46, v145
	v_fmac_f32_e32 v31, v47, v145
	s_mov_b32 s0, s68
	s_mov_b32 s1, s69
	global_store_dword v221, v189, s[0:1]
	global_store_dword v221, v205, s[0:1] offset:128
	s_add_u32 s0, s68, 0x1000
	s_addc_u32 s1, s69, 0
	global_store_dword v221, v190, s[0:1]
	global_store_dword v221, v206, s[0:1] offset:128
	s_add_u32 s0, s68, 0x2000
	s_addc_u32 s1, s69, 0
	global_store_dword v221, v191, s[0:1]
	global_store_dword v221, v207, s[0:1] offset:128
	s_add_u32 s0, s68, 0x3000
	s_addc_u32 s1, s69, 0
	global_store_dword v221, v192, s[0:1]
	global_store_dword v221, v208, s[0:1] offset:128
	s_add_u32 s0, s68, 0x8000
	s_addc_u32 s1, s69, 0
	global_store_dword v221, v193, s[0:1]
	global_store_dword v221, v209, s[0:1] offset:128
	s_add_u32 s0, s68, 0x9000
	s_addc_u32 s1, s69, 0
	global_store_dword v221, v194, s[0:1]
	global_store_dword v221, v210, s[0:1] offset:128
	s_add_u32 s0, s68, 0xa000
	s_addc_u32 s1, s69, 0
	global_store_dword v221, v195, s[0:1]
	global_store_dword v221, v211, s[0:1] offset:128
	s_add_u32 s0, s68, 0xb000
	s_addc_u32 s1, s69, 0
	global_store_dword v221, v196, s[0:1]
	global_store_dword v221, v212, s[0:1] offset:128
	s_add_u32 s0, s68, 0x10000
	s_addc_u32 s1, s69, 0
	global_store_dword v221, v197, s[0:1]
	global_store_dword v221, v213, s[0:1] offset:128
	s_add_u32 s0, s68, 0x11000
	s_addc_u32 s1, s69, 0
	global_store_dword v221, v198, s[0:1]
	global_store_dword v221, v214, s[0:1] offset:128
	s_add_u32 s0, s68, 0x12000
	s_addc_u32 s1, s69, 0
	global_store_dword v221, v199, s[0:1]
	global_store_dword v221, v215, s[0:1] offset:128
	s_add_u32 s0, s68, 0x13000
	s_addc_u32 s1, s69, 0
	global_store_dword v221, v200, s[0:1]
	global_store_dword v221, v216, s[0:1] offset:128
	s_add_u32 s0, s68, 0x18000
	s_addc_u32 s1, s69, 0
	global_store_dword v221, v201, s[0:1]
	global_store_dword v221, v217, s[0:1] offset:128
	s_add_u32 s0, s68, 0x19000
	s_addc_u32 s1, s69, 0
	global_store_dword v221, v202, s[0:1]
	global_store_dword v221, v218, s[0:1] offset:128
	s_add_u32 s0, s68, 0x1a000
	s_addc_u32 s1, s69, 0
	global_store_dword v221, v203, s[0:1]
	global_store_dword v221, v219, s[0:1] offset:128
	s_add_u32 s0, s68, 0x1b000
	s_addc_u32 s1, s69, 0
	global_store_dword v221, v204, s[0:1]
	global_store_dword v221, v220, s[0:1] offset:128
	s_add_u32 s0, s68, 0x20000
	s_addc_u32 s1, s69, 0
	global_store_dword v221, v150, s[0:1]
	global_store_dword v221, v172, s[0:1] offset:128
	s_add_u32 s0, s68, 0x21000
	s_addc_u32 s1, s69, 0
	global_store_dword v221, v151, s[0:1]
	global_store_dword v221, v173, s[0:1] offset:128
	s_add_u32 s0, s68, 0x22000
	s_addc_u32 s1, s69, 0
	global_store_dword v221, v152, s[0:1]
	global_store_dword v221, v174, s[0:1] offset:128
	s_add_u32 s0, s68, 0x23000
	s_addc_u32 s1, s69, 0
	global_store_dword v221, v153, s[0:1]
	global_store_dword v221, v175, s[0:1] offset:128
	s_add_u32 s0, s68, 0x28000
	s_addc_u32 s1, s69, 0
	global_store_dword v221, v154, s[0:1]
	global_store_dword v221, v176, s[0:1] offset:128
	s_add_u32 s0, s68, 0x29000
	s_addc_u32 s1, s69, 0
	global_store_dword v221, v155, s[0:1]
	global_store_dword v221, v177, s[0:1] offset:128
	s_add_u32 s0, s68, 0x2a000
	s_addc_u32 s1, s69, 0
	global_store_dword v221, v156, s[0:1]
	global_store_dword v221, v178, s[0:1] offset:128
	s_add_u32 s0, s68, 0x2b000
	s_addc_u32 s1, s69, 0
	global_store_dword v221, v157, s[0:1]
	global_store_dword v221, v179, s[0:1] offset:128
	s_add_u32 s0, s68, 0x30000
	s_addc_u32 s1, s69, 0
	global_store_dword v221, v158, s[0:1]
	global_store_dword v221, v180, s[0:1] offset:128
	s_add_u32 s0, s68, 0x31000
	s_addc_u32 s1, s69, 0
	global_store_dword v221, v159, s[0:1]
	global_store_dword v221, v181, s[0:1] offset:128
	s_add_u32 s0, s68, 0x32000
	s_addc_u32 s1, s69, 0
	global_store_dword v221, v160, s[0:1]
	global_store_dword v221, v182, s[0:1] offset:128
	s_add_u32 s0, s68, 0x33000
	s_addc_u32 s1, s69, 0
	global_store_dword v221, v161, s[0:1]
	global_store_dword v221, v183, s[0:1] offset:128
	s_add_u32 s0, s68, 0x38000
	s_addc_u32 s1, s69, 0
	global_store_dword v221, v162, s[0:1]
	global_store_dword v221, v184, s[0:1] offset:128
	s_add_u32 s0, s68, 0x39000
	s_addc_u32 s1, s69, 0
	global_store_dword v221, v163, s[0:1]
	global_store_dword v221, v185, s[0:1] offset:128
	s_add_u32 s0, s68, 0x3a000
	s_addc_u32 s1, s69, 0
	global_store_dword v221, v164, s[0:1]
	global_store_dword v221, v186, s[0:1] offset:128
	s_add_u32 s0, s68, 0x3b000
	s_addc_u32 s1, s69, 0
	global_store_dword v221, v165, s[0:1]
	global_store_dword v221, v187, s[0:1] offset:128
	s_add_u32 s0, s68, 0x40000
	s_addc_u32 s1, s69, 0
	global_store_dword v221, v0, s[0:1]
	global_store_dword v221, v16, s[0:1] offset:128
	s_add_u32 s0, s68, 0x41000
	s_addc_u32 s1, s69, 0
	global_store_dword v221, v1, s[0:1]
	global_store_dword v221, v17, s[0:1] offset:128
	s_add_u32 s0, s68, 0x42000
	s_addc_u32 s1, s69, 0
	global_store_dword v221, v2, s[0:1]
	global_store_dword v221, v18, s[0:1] offset:128
	s_add_u32 s0, s68, 0x43000
	s_addc_u32 s1, s69, 0
	global_store_dword v221, v3, s[0:1]
	global_store_dword v221, v19, s[0:1] offset:128
	s_add_u32 s0, s68, 0x48000
	s_addc_u32 s1, s69, 0
	global_store_dword v221, v4, s[0:1]
	global_store_dword v221, v20, s[0:1] offset:128
	s_add_u32 s0, s68, 0x49000
	s_addc_u32 s1, s69, 0
	global_store_dword v221, v5, s[0:1]
	global_store_dword v221, v21, s[0:1] offset:128
	s_add_u32 s0, s68, 0x4a000
	s_addc_u32 s1, s69, 0
	global_store_dword v221, v6, s[0:1]
	global_store_dword v221, v22, s[0:1] offset:128
	s_add_u32 s0, s68, 0x4b000
	s_addc_u32 s1, s69, 0
	global_store_dword v221, v7, s[0:1]
	global_store_dword v221, v23, s[0:1] offset:128
	s_add_u32 s0, s68, 0x50000
	s_addc_u32 s1, s69, 0
	global_store_dword v221, v8, s[0:1]
	global_store_dword v221, v24, s[0:1] offset:128
	s_add_u32 s0, s68, 0x51000
	s_addc_u32 s1, s69, 0
	global_store_dword v221, v9, s[0:1]
	global_store_dword v221, v25, s[0:1] offset:128
	s_add_u32 s0, s68, 0x52000
	s_addc_u32 s1, s69, 0
	global_store_dword v221, v10, s[0:1]
	global_store_dword v221, v26, s[0:1] offset:128
	s_add_u32 s0, s68, 0x53000
	s_addc_u32 s1, s69, 0
	global_store_dword v221, v11, s[0:1]
	global_store_dword v221, v27, s[0:1] offset:128
	s_add_u32 s0, s68, 0x58000
	s_addc_u32 s1, s69, 0
	global_store_dword v221, v12, s[0:1]
	global_store_dword v221, v28, s[0:1] offset:128
	s_add_u32 s0, s68, 0x59000
	s_addc_u32 s1, s69, 0
	global_store_dword v221, v13, s[0:1]
	global_store_dword v221, v29, s[0:1] offset:128
	s_add_u32 s0, s68, 0x5a000
	s_addc_u32 s1, s69, 0
	global_store_dword v221, v14, s[0:1]
	global_store_dword v221, v30, s[0:1] offset:128
	s_add_u32 s0, s68, 0x5b000
	s_addc_u32 s1, s69, 0
	global_store_dword v221, v15, s[0:1]
	global_store_dword v221, v31, s[0:1] offset:128
	s_andn2_b64 exec, exec, s[46:47]
	s_cbranch_execz .LBB0_237
.LBB0_225:
	v_mov_b32_e32 v32, v224
	v_mov_b32_e32 v170, v146
	v_and_b32_e32 v0, 31, v32
	v_lshrrev_b32_e32 v1, 1, v32
	v_lshrrev_b32_e32 v1, 8, v32
	v_mul_u32_u24_e32 v1, 0x60, v1
	v_add_u32_e32 v0, v1, v0
	v_lshlrev_b32_e32 v182, 7, v0
	v_lshlrev_b32_e32 v0, 7, v32
	v_and_b32_e32 v183, 0x6f80, v0
	v_lshrrev_b32_e32 v0, 5, v32
	v_bfe_u32 v2, v32, 1, 3
	v_bfe_u32 v1, v32, 5, 1
	v_bitop3_b32 v0, v0, v2, 1 bitop3:0x6c
	v_lshlrev_b32_e32 v184, 4, v0
	v_bitop3_b32 v0, v1, v2, 2 bitop3:0x36
	v_lshlrev_b32_e32 v181, 4, v0
	v_bitop3_b32 v0, v1, v2, 4 bitop3:0x36
	v_ashrrev_i32_e32 v188, 3, v32
	v_add_u32_e32 v3, 0x200, v32
	v_add_u32_e32 v4, 0x400, v32
	v_add_u32_e32 v5, 0x600, v32
	v_lshlrev_b32_e32 v172, 4, v0
	v_bitop3_b32 v0, v1, v2, 6 bitop3:0x36
	v_mov_b32_e32 v169, v148
	s_movk_i32 s0, 0xff
	v_lshrrev_b32_e32 v33, 4, v32
	v_ashrrev_i32_e32 v187, 3, v3
	v_ashrrev_i32_e32 v186, 3, v4
	v_ashrrev_i32_e32 v185, 3, v5
	v_lshrrev_b32_e32 v176, 3, v32
	v_lshrrev_b32_e32 v175, 3, v3
	v_lshrrev_b32_e32 v174, 3, v4
	v_lshrrev_b32_e32 v173, 3, v5
	v_lshlrev_b32_e32 v171, 4, v0
	v_add_u32_e32 v0, v188, v170
	v_cmp_gt_i32_e32 vcc, s73, v32
	v_cmp_lt_i32_e64 s[0:1], s0, v32
	v_xor_b32_e32 v132, v33, v32
	v_lshlrev_b32_e32 v180, 4, v32
	v_lshlrev_b32_e32 v178, 4, v4
	v_ashrrev_i32_e32 v1, 31, v0
	v_add_u32_e32 v2, v187, v170
	v_add_u32_e32 v4, v186, v170
	v_add_u32_e32 v6, v185, v170
	v_add_u32_e32 v8, v176, v170
	v_add_u32_e32 v10, v175, v170
	v_add_u32_e32 v12, v174, v170
	v_add_u32_e32 v14, v173, v170
	v_add_u32_e32 v16, v188, v169
	v_add_u32_e32 v18, v187, v169
	v_add_u32_e32 v20, v186, v169
	v_add_u32_e32 v22, v185, v169
	v_add_u32_e32 v24, v176, v169
	v_add_u32_e32 v26, v175, v169
	v_add_u32_e32 v28, v174, v169
	v_add_u32_e32 v30, v173, v169
	v_bitop3_b32 v32, v33, 7, v32 bitop3:0x48
	v_lshlrev_b32_e32 v179, 4, v3
	v_lshlrev_b32_e32 v177, 4, v5
	v_ashrrev_i32_e32 v3, 31, v2
	v_ashrrev_i32_e32 v5, 31, v4
	v_ashrrev_i32_e32 v7, 31, v6
	v_ashrrev_i32_e32 v9, 31, v8
	v_ashrrev_i32_e32 v11, 31, v10
	v_ashrrev_i32_e32 v13, 31, v12
	v_ashrrev_i32_e32 v15, 31, v14
	v_lshlrev_b64 v[0:1], 13, v[0:1]
	v_ashrrev_i32_e32 v17, 31, v16
	v_ashrrev_i32_e32 v19, 31, v18
	v_ashrrev_i32_e32 v21, 31, v20
	v_ashrrev_i32_e32 v23, 31, v22
	v_ashrrev_i32_e32 v25, 31, v24
	v_ashrrev_i32_e32 v27, 31, v26
	v_ashrrev_i32_e32 v29, 31, v28
	v_ashrrev_i32_e32 v31, 31, v30
	v_lshlrev_b32_e32 v32, 4, v32
	s_waitcnt vmcnt(0)
	v_lshlrev_b64 v[2:3], 13, v[2:3]
	v_lshlrev_b64 v[4:5], 13, v[4:5]
	v_lshlrev_b64 v[6:7], 13, v[6:7]
	v_lshlrev_b64 v[8:9], 13, v[8:9]
	v_lshlrev_b64 v[10:11], 13, v[10:11]
	v_lshlrev_b64 v[12:13], 13, v[12:13]
	v_lshlrev_b64 v[14:15], 13, v[14:15]
	v_lshlrev_b64 v[16:17], 13, v[16:17]
	v_lshlrev_b64 v[18:19], 13, v[18:19]
	v_lshlrev_b64 v[20:21], 13, v[20:21]
	v_lshlrev_b64 v[22:23], 13, v[22:23]
	v_lshlrev_b64 v[24:25], 13, v[24:25]
	v_lshlrev_b64 v[26:27], 13, v[26:27]
	v_lshlrev_b64 v[28:29], 13, v[28:29]
	v_lshlrev_b64 v[30:31], 13, v[30:31]
	v_or_b32_e32 v0, v0, v32
	v_lshl_add_u64 v[134:135], s[42:43], 0, v[0:1]
	v_or_b32_e32 v2, v2, v32
	v_or_b32_e32 v4, v4, v32
	v_or_b32_e32 v6, v6, v32
	v_or_b32_e32 v16, v16, v32
	v_or_b32_e32 v18, v18, v32
	v_or_b32_e32 v20, v20, v32
	v_or_b32_e32 v22, v22, v32
	v_or_b32_e32 v8, v8, v32
	v_or_b32_e32 v10, v10, v32
	v_or_b32_e32 v12, v12, v32
	v_or_b32_e32 v14, v14, v32
	v_or_b32_e32 v24, v24, v32
	v_or_b32_e32 v26, v26, v32
	v_or_b32_e32 v28, v28, v32
	v_or_b32_e32 v30, v30, v32
	v_mov_b32_e32 v0, 0
	v_mov_b32_e32 v128, v147
	v_lshl_add_u64 v[136:137], s[42:43], 0, v[2:3]
	v_lshl_add_u64 v[138:139], s[42:43], 0, v[4:5]
	v_lshl_add_u64 v[140:141], s[42:43], 0, v[6:7]
	v_lshl_add_u64 v[142:143], s[44:45], 0, v[16:17]
	v_lshl_add_u64 v[144:145], s[44:45], 0, v[18:19]
	v_lshl_add_u64 v[146:147], s[44:45], 0, v[20:21]
	v_lshl_add_u64 v[148:149], s[44:45], 0, v[22:23]
	v_lshl_add_u64 v[150:151], s[42:43], 0, v[8:9]
	v_lshl_add_u64 v[152:153], s[42:43], 0, v[10:11]
	v_lshl_add_u64 v[154:155], s[42:43], 0, v[12:13]
	v_lshl_add_u64 v[156:157], s[42:43], 0, v[14:15]
	v_lshl_add_u64 v[158:159], s[44:45], 0, v[24:25]
	v_lshl_add_u64 v[160:161], s[44:45], 0, v[26:27]
	v_lshl_add_u64 v[162:163], s[44:45], 0, v[28:29]
	v_lshl_add_u64 v[164:165], s[44:45], 0, v[30:31]
	s_mov_b64 s[4:5], 0
	v_mov_b32_e32 v1, v0
	v_mov_b32_e32 v2, v0
	v_mov_b32_e32 v3, v0
	v_mov_b32_e32 v4, v0
	v_mov_b32_e32 v5, v0
	v_mov_b32_e32 v6, v0
	v_mov_b32_e32 v7, v0
	v_mov_b32_e32 v8, v0
	v_mov_b32_e32 v9, v0
	v_mov_b32_e32 v10, v0
	v_mov_b32_e32 v11, v0
	v_mov_b32_e32 v12, v0
	v_mov_b32_e32 v13, v0
	v_mov_b32_e32 v14, v0
	v_mov_b32_e32 v15, v0
	v_mov_b32_e32 v16, v0
	v_mov_b32_e32 v17, v0
	v_mov_b32_e32 v18, v0
	v_mov_b32_e32 v19, v0
	v_mov_b32_e32 v20, v0
	v_mov_b32_e32 v21, v0
	v_mov_b32_e32 v22, v0
	v_mov_b32_e32 v23, v0
	v_mov_b32_e32 v24, v0
	v_mov_b32_e32 v25, v0
	v_mov_b32_e32 v26, v0
	v_mov_b32_e32 v27, v0
	v_mov_b32_e32 v28, v0
	v_mov_b32_e32 v29, v0
	v_mov_b32_e32 v30, v0
	v_mov_b32_e32 v31, v0
	v_mov_b32_e32 v32, v0
	v_mov_b32_e32 v33, v0
	v_mov_b32_e32 v34, v0
	v_mov_b32_e32 v35, v0
	v_mov_b32_e32 v36, v0
	v_mov_b32_e32 v37, v0
	v_mov_b32_e32 v38, v0
	v_mov_b32_e32 v39, v0
	v_mov_b32_e32 v40, v0
	v_mov_b32_e32 v41, v0
	v_mov_b32_e32 v42, v0
	v_mov_b32_e32 v43, v0
	v_mov_b32_e32 v44, v0
	v_mov_b32_e32 v45, v0
	v_mov_b32_e32 v46, v0
	v_mov_b32_e32 v47, v0
	v_mov_b32_e32 v48, v0
	v_mov_b32_e32 v49, v0
	v_mov_b32_e32 v50, v0
	v_mov_b32_e32 v51, v0
	v_mov_b32_e32 v52, v0
	v_mov_b32_e32 v53, v0
	v_mov_b32_e32 v54, v0
	v_mov_b32_e32 v55, v0
	v_mov_b32_e32 v56, v0
	v_mov_b32_e32 v57, v0
	v_mov_b32_e32 v58, v0
	v_mov_b32_e32 v59, v0
	v_mov_b32_e32 v60, v0
	v_mov_b32_e32 v61, v0
	v_mov_b32_e32 v62, v0
	v_mov_b32_e32 v63, v0
	v_mov_b32_e32 v64, v0
	v_mov_b32_e32 v65, v0
	v_mov_b32_e32 v66, v0
	v_mov_b32_e32 v67, v0
	v_mov_b32_e32 v68, v0
	v_mov_b32_e32 v69, v0
	v_mov_b32_e32 v70, v0
	v_mov_b32_e32 v71, v0
	v_mov_b32_e32 v72, v0
	v_mov_b32_e32 v73, v0
	v_mov_b32_e32 v74, v0
	v_mov_b32_e32 v75, v0
	v_mov_b32_e32 v76, v0
	v_mov_b32_e32 v77, v0
	v_mov_b32_e32 v78, v0
	v_mov_b32_e32 v79, v0
	v_mov_b32_e32 v80, v0
	v_mov_b32_e32 v81, v0
	v_mov_b32_e32 v82, v0
	v_mov_b32_e32 v83, v0
	v_mov_b32_e32 v84, v0
	v_mov_b32_e32 v85, v0
	v_mov_b32_e32 v86, v0
	v_mov_b32_e32 v87, v0
	v_mov_b32_e32 v88, v0
	v_mov_b32_e32 v89, v0
	v_mov_b32_e32 v90, v0
	v_mov_b32_e32 v91, v0
	v_mov_b32_e32 v92, v0
	v_mov_b32_e32 v93, v0
	v_mov_b32_e32 v94, v0
	v_mov_b32_e32 v95, v0
	v_mov_b32_e32 v96, v0
	v_mov_b32_e32 v97, v0
	v_mov_b32_e32 v98, v0
	v_mov_b32_e32 v99, v0
	v_mov_b32_e32 v100, v0
	v_mov_b32_e32 v101, v0
	v_mov_b32_e32 v102, v0
	v_mov_b32_e32 v103, v0
	v_mov_b32_e32 v104, v0
	v_mov_b32_e32 v105, v0
	v_mov_b32_e32 v106, v0
	v_mov_b32_e32 v107, v0
	v_mov_b32_e32 v108, v0
	v_mov_b32_e32 v109, v0
	v_mov_b32_e32 v110, v0
	v_mov_b32_e32 v111, v0
	v_mov_b32_e32 v112, v0
	v_mov_b32_e32 v113, v0
	v_mov_b32_e32 v114, v0
	v_mov_b32_e32 v115, v0
	v_mov_b32_e32 v116, v0
	v_mov_b32_e32 v117, v0
	v_mov_b32_e32 v118, v0
	v_mov_b32_e32 v119, v0
	v_mov_b32_e32 v120, v0
	v_mov_b32_e32 v121, v0
	v_mov_b32_e32 v122, v0
	v_mov_b32_e32 v123, v0
	v_mov_b32_e32 v124, v0
	v_mov_b32_e32 v125, v0
	v_mov_b32_e32 v126, v0
	v_mov_b32_e32 v127, v0
	s_waitcnt vmcnt(0)
	s_barrier
	s_lshl_b32 s13, s9, 16
	s_and_saveexec_b64 s[6:7], vcc
	s_cbranch_execz .LBB0_228
	s_branch .LBB0_227

.LBB0_227:
	s_xor_b32 s14, s13, 0x10000
	s_add_i32 s14, s14, 0
	v_add_u32_e32 v133, s14, v180
	v_add_u32_e32 v189, s14, v179
	v_readfirstlane_b32 s15, v133
	v_lshl_add_u64 v[130:131], v[134:135], 0, s[4:5]
	s_mov_b32 m0, s15
	v_readfirstlane_b32 s15, v189
	v_add_u32_e32 v190, s14, v178
	global_load_lds_dwordx4 v[130:131], off
	v_lshl_add_u64 v[130:131], v[136:137], 0, s[4:5]
	s_mov_b32 m0, s15
	v_readfirstlane_b32 s15, v190
	v_add_u32_e32 v191, s14, v177
	global_load_lds_dwordx4 v[130:131], off
	v_lshl_add_u64 v[130:131], v[138:139], 0, s[4:5]
	s_mov_b32 m0, s15
	v_readfirstlane_b32 s14, v191
	v_add_u32_e32 v133, 0x8000, v133
	global_load_lds_dwordx4 v[130:131], off
	v_readfirstlane_b32 s14, v133
	v_add_u32_e32 v133, 0x8000, v189
	v_lshl_add_u64 v[130:131], v[142:143], 0, s[4:5]
	s_mov_b32 m0, s14
	v_readfirstlane_b32 s14, v133
	v_add_u32_e32 v133, 0x8000, v190
	global_load_lds_dwordx4 v[130:131], off
	v_lshl_add_u64 v[130:131], v[144:145], 0, s[4:5]
	s_mov_b32 m0, s14
	v_readfirstlane_b32 s14, v133
	v_add_u32_e32 v133, 0x8000, v191
	global_load_lds_dwordx4 v[130:131], off
	v_lshl_add_u64 v[130:131], v[146:147], 0, s[4:5]
	s_mov_b32 m0, s14
	v_readfirstlane_b32 s14, v133
	global_load_lds_dwordx4 v[130:131], off
	v_lshl_add_u64 v[130:131], v[148:149], 0, s[4:5]
	s_mov_b32 m0, s14
	s_nop 0
	global_load_lds_dwordx4 v[130:131], off
.LBB0_228:
	s_or_b64 exec, exec, s[6:7]
	s_add_i32 s6, s13, 0
	v_add_u32_e32 v131, s6, v182
	v_add_u32_e32 v133, v131, v184
	v_add_u32_e32 v130, s6, v183
	ds_read_b128 v[190:193], v133
	ds_read_b128 v[194:197], v133 offset:4096
	ds_read_b128 v[198:201], v133 offset:8192
	v_add_u32_e32 v133, v130, v184
	ds_read_b128 v[206:209], v133 offset:32768
	ds_read_b128 v[210:213], v133 offset:36864
	s_setprio 1
	s_waitcnt lgkmcnt(0)
	v_mfma_f32_32x32x16_bf16 v[112:127], v[190:193], v[206:209], v[112:127]
	v_mfma_f32_32x32x16_bf16 v[96:111], v[190:193], v[210:213], v[96:111]
	v_mfma_f32_32x32x16_bf16 v[80:95], v[194:197], v[206:209], v[80:95]
	v_mfma_f32_32x32x16_bf16 v[64:79], v[194:197], v[210:213], v[64:79]
	v_mfma_f32_32x32x16_bf16 v[48:63], v[198:201], v[206:209], v[48:63]
	v_mfma_f32_32x32x16_bf16 v[32:47], v[198:201], v[210:213], v[32:47]
	s_setprio 0
	v_add_u32_e32 v133, v131, v181
	ds_read_b128 v[190:193], v133
	ds_read_b128 v[194:197], v133 offset:4096
	ds_read_b128 v[198:201], v133 offset:8192
	v_add_u32_e32 v133, v130, v181
	ds_read_b128 v[206:209], v133 offset:32768
	ds_read_b128 v[210:213], v133 offset:36864
	s_setprio 1
	s_waitcnt lgkmcnt(0)
	v_mfma_f32_32x32x16_bf16 v[112:127], v[190:193], v[206:209], v[112:127]
	v_mfma_f32_32x32x16_bf16 v[96:111], v[190:193], v[210:213], v[96:111]
	v_mfma_f32_32x32x16_bf16 v[80:95], v[194:197], v[206:209], v[80:95]
	v_mfma_f32_32x32x16_bf16 v[64:79], v[194:197], v[210:213], v[64:79]
	v_mfma_f32_32x32x16_bf16 v[48:63], v[198:201], v[206:209], v[48:63]
	v_mfma_f32_32x32x16_bf16 v[32:47], v[198:201], v[210:213], v[32:47]
	s_setprio 0
	s_and_saveexec_b64 s[6:7], s[0:1]
	s_cbranch_execz .LBB0_230
	s_xor_b32 s13, s13, 0x10000
	s_add_i32 s13, s13, 0
	v_add_u32_e32 v133, s13, v180
	v_add_u32_e32 v189, s13, v179
	v_readfirstlane_b32 s14, v133
	v_lshl_add_u64 v[190:191], v[150:151], 0, s[4:5]
	s_mov_b32 m0, s14
	v_readfirstlane_b32 s14, v189
	v_add_u32_e32 v192, s13, v178
	global_load_lds_dwordx4 v[190:191], off
	v_lshl_add_u64 v[190:191], v[152:153], 0, s[4:5]
	s_mov_b32 m0, s14
	v_readfirstlane_b32 s14, v192
	v_add_u32_e32 v193, s13, v177
	global_load_lds_dwordx4 v[190:191], off
	v_lshl_add_u64 v[190:191], v[154:155], 0, s[4:5]
	s_mov_b32 m0, s14
	v_readfirstlane_b32 s13, v193
	v_add_u32_e32 v133, 0x8000, v133
	global_load_lds_dwordx4 v[190:191], off
	v_readfirstlane_b32 s13, v133
	v_add_u32_e32 v133, 0x8000, v189
	v_lshl_add_u64 v[190:191], v[158:159], 0, s[4:5]
	s_mov_b32 m0, s13
	v_readfirstlane_b32 s13, v133
	v_add_u32_e32 v133, 0x8000, v192
	global_load_lds_dwordx4 v[190:191], off
	v_lshl_add_u64 v[190:191], v[160:161], 0, s[4:5]
	s_mov_b32 m0, s13
	v_readfirstlane_b32 s13, v133
	v_add_u32_e32 v133, 0x8000, v193
	global_load_lds_dwordx4 v[190:191], off
	v_lshl_add_u64 v[190:191], v[162:163], 0, s[4:5]
	s_mov_b32 m0, s13
	v_readfirstlane_b32 s13, v133
	global_load_lds_dwordx4 v[190:191], off
	v_lshl_add_u64 v[190:191], v[164:165], 0, s[4:5]
	s_mov_b32 m0, s13
	s_nop 0
	global_load_lds_dwordx4 v[190:191], off
.LBB0_230:
	s_or_b64 exec, exec, s[6:7]
	v_add_u32_e32 v133, v131, v172
	ds_read_b128 v[190:193], v133
	ds_read_b128 v[194:197], v133 offset:4096
	ds_read_b128 v[198:201], v133 offset:8192
	v_add_u32_e32 v133, v130, v172
	ds_read_b128 v[206:209], v133 offset:32768
	ds_read_b128 v[210:213], v133 offset:36864
	s_setprio 1
	s_waitcnt lgkmcnt(0)
	v_mfma_f32_32x32x16_bf16 v[112:127], v[190:193], v[206:209], v[112:127]
	v_mfma_f32_32x32x16_bf16 v[96:111], v[190:193], v[210:213], v[96:111]
	v_mfma_f32_32x32x16_bf16 v[80:95], v[194:197], v[206:209], v[80:95]
	v_mfma_f32_32x32x16_bf16 v[64:79], v[194:197], v[210:213], v[64:79]
	v_mfma_f32_32x32x16_bf16 v[48:63], v[198:201], v[206:209], v[48:63]
	v_mfma_f32_32x32x16_bf16 v[32:47], v[198:201], v[210:213], v[32:47]
	s_setprio 0
	v_add_u32_e32 v131, v131, v171
	ds_read_b128 v[190:193], v131
	ds_read_b128 v[194:197], v131 offset:4096
	ds_read_b128 v[198:201], v131 offset:8192
	v_add_u32_e32 v130, v130, v171
	ds_read_b128 v[206:209], v130 offset:32768
	ds_read_b128 v[210:213], v130 offset:36864
	s_setprio 1
	s_waitcnt lgkmcnt(0)
	v_mfma_f32_32x32x16_bf16 v[112:127], v[190:193], v[206:209], v[112:127]
	v_mfma_f32_32x32x16_bf16 v[96:111], v[190:193], v[210:213], v[96:111]
	v_mfma_f32_32x32x16_bf16 v[80:95], v[194:197], v[206:209], v[80:95]
	v_mfma_f32_32x32x16_bf16 v[64:79], v[194:197], v[210:213], v[64:79]
	v_mfma_f32_32x32x16_bf16 v[48:63], v[198:201], v[206:209], v[48:63]
	v_mfma_f32_32x32x16_bf16 v[32:47], v[198:201], v[210:213], v[32:47]
	s_setprio 0
	s_xor_b32 s6, s9, 1
	s_waitcnt vmcnt(0)
	s_add_u32 s4, s4, 0x80
	s_addc_u32 s5, s5, 0
	s_cmpk_lg_i32 s4, 0x1f80
	s_waitcnt vmcnt(0)
	s_barrier
	s_cbranch_scc1 .LBB0_226
	v_add_u32_e32 v147, s8, v128
	v_cmp_lt_i32_e64 s[0:1], 31, v147
	s_xor_b64 s[4:5], vcc, -1
	s_nor_b64 s[4:5], s[4:5], s[0:1]
	v_cndmask_b32_e64 v128, v147, v128, s[0:1]
	v_ashrrev_i32_e32 v130, 31, v128
	v_lshrrev_b32_e32 v130, 30, v130
	v_add_u32_e32 v130, v128, v130
	v_lshrrev_b32_e32 v131, 2, v130
	v_and_b32_e32 v130, 0xfffffc, v130
	v_sub_u32_e32 v130, v128, v130
	v_lshlrev_b32_e32 v128, 4, v132
	v_and_b32_e32 v128, 0x70, v128
	v_add_lshl_u32 v146, v131, v166, 8
	v_lshl_add_u64 v[136:137], s[38:39], 0, v[128:129]
	v_lshl_add_u64 v[134:135], s[40:41], 0, v[128:129]
	v_lshlrev_b32_e32 v148, 8, v130
	s_and_saveexec_b64 s[14:15], s[4:5]
	s_xor_b64 s[4:5], exec, s[14:15]
	s_cbranch_execz .LBB0_233
	s_lshl_b32 s7, s6, 16
	s_xor_b32 s13, s7, 0x10000
	v_add_u32_e32 v130, v146, v188
	s_add_i32 s13, s13, 0
	v_ashrrev_i32_e32 v131, 31, v130
	v_add_u32_e32 v132, v187, v146
	v_add_u32_e32 v128, s13, v180
	v_lshlrev_b64 v[130:131], 13, v[130:131]
	v_ashrrev_i32_e32 v133, 31, v132
	v_readfirstlane_b32 s14, v128
	v_add_u32_e32 v142, s13, v179
	v_lshl_add_u64 v[130:131], v[136:137], 0, v[130:131]
	v_lshlrev_b64 v[132:133], 13, v[132:133]
	s_mov_b32 m0, s14
	v_readfirstlane_b32 s14, v142
	v_lshl_add_u64 v[132:133], v[136:137], 0, v[132:133]
	v_add_u32_e32 v138, v186, v146
	global_load_lds_dwordx4 v[130:131], off
	s_mov_b32 m0, s14
	v_ashrrev_i32_e32 v139, 31, v138
	v_add_u32_e32 v140, v185, v146
	global_load_lds_dwordx4 v[132:133], off
	v_add_u32_e32 v132, s13, v178
	v_lshlrev_b64 v[138:139], 13, v[138:139]
	v_ashrrev_i32_e32 v141, 31, v140
	v_readfirstlane_b32 s14, v132
	v_add_u32_e32 v133, s13, v177
	v_add_u32_e32 v130, v148, v188
	v_lshl_add_u64 v[138:139], v[136:137], 0, v[138:139]
	v_lshlrev_b64 v[140:141], 13, v[140:141]
	s_mov_b32 m0, s14
	v_readfirstlane_b32 s13, v133
	v_ashrrev_i32_e32 v131, 31, v130
	v_add_u32_e32 v128, 0x8000, v128
	v_lshl_add_u64 v[140:141], v[136:137], 0, v[140:141]
	global_load_lds_dwordx4 v[138:139], off
	s_mov_b32 m0, s13
	v_lshlrev_b64 v[130:131], 13, v[130:131]
	v_readfirstlane_b32 s13, v128
	global_load_lds_dwordx4 v[140:141], off
	v_lshl_add_u64 v[130:131], v[134:135], 0, v[130:131]
	s_mov_b32 m0, s13
	v_add_u32_e32 v128, 0x8000, v142
	global_load_lds_dwordx4 v[130:131], off
	v_add_u32_e32 v130, v187, v148
	v_ashrrev_i32_e32 v131, 31, v130
	v_lshlrev_b64 v[130:131], 13, v[130:131]
	v_readfirstlane_b32 s13, v128
	v_lshl_add_u64 v[130:131], v[134:135], 0, v[130:131]
	s_mov_b32 m0, s13
	v_add_u32_e32 v128, 0x8000, v132
	global_load_lds_dwordx4 v[130:131], off
	v_add_u32_e32 v130, v186, v148
	v_ashrrev_i32_e32 v131, 31, v130
	v_lshlrev_b64 v[130:131], 13, v[130:131]
	v_readfirstlane_b32 s13, v128
	v_lshl_add_u64 v[130:131], v[134:135], 0, v[130:131]
	s_mov_b32 m0, s13
	v_add_u32_e32 v128, 0x8000, v133
	global_load_lds_dwordx4 v[130:131], off
	v_add_u32_e32 v130, v185, v148
	v_ashrrev_i32_e32 v131, 31, v130
	v_lshlrev_b64 v[130:131], 13, v[130:131]
	v_readfirstlane_b32 s13, v128
	v_lshl_add_u64 v[130:131], v[134:135], 0, v[130:131]
	s_mov_b32 m0, s13
	s_nop 0
	global_load_lds_dwordx4 v[130:131], off
.LBB0_233:
	s_or_saveexec_b64 s[4:5], s[4:5]
	v_mov_b32_e32 v131, s7
	s_xor_b64 exec, exec, s[4:5]
	s_lshl_b32 s6, s6, 16
	v_mov_b32_e32 v131, s6
	s_or_b64 exec, exec, s[4:5]
	v_add_u32_e32 v128, 0, v131
	v_add_u32_e32 v130, v128, v182
	v_add_u32_e32 v132, v130, v184
	v_add_u32_e32 v128, v128, v183
	ds_read_b128 v[138:141], v132
	ds_read_b128 v[142:145], v132 offset:4096
	ds_read_b128 v[150:153], v132 offset:8192
	v_add_u32_e32 v132, v128, v184
	ds_read_b128 v[158:161], v132 offset:32768
	ds_read_b128 v[162:165], v132 offset:36864
	s_and_b64 s[4:5], exec, s[0:1]
	s_or_b64 s[46:47], s[4:5], s[46:47]
	s_setprio 1
	s_waitcnt lgkmcnt(0)
	v_mfma_f32_32x32x16_bf16 v[112:127], v[138:141], v[158:161], v[112:127]
	v_mfma_f32_32x32x16_bf16 v[96:111], v[138:141], v[162:165], v[96:111]
	v_mfma_f32_32x32x16_bf16 v[80:95], v[142:145], v[158:161], v[80:95]
	v_mfma_f32_32x32x16_bf16 v[64:79], v[142:145], v[162:165], v[64:79]
	v_mfma_f32_32x32x16_bf16 v[48:63], v[150:153], v[158:161], v[48:63]
	v_mfma_f32_32x32x16_bf16 v[32:47], v[150:153], v[162:165], v[32:47]
	s_setprio 0
	v_add_u32_e32 v132, v130, v181
	ds_read_b128 v[138:141], v132
	ds_read_b128 v[142:145], v132 offset:4096
	ds_read_b128 v[150:153], v132 offset:8192
	v_add_u32_e32 v132, v128, v181
	ds_read_b128 v[158:161], v132 offset:32768
	ds_read_b128 v[162:165], v132 offset:36864
	s_setprio 1
	s_waitcnt lgkmcnt(0)
	v_mfma_f32_32x32x16_bf16 v[112:127], v[138:141], v[158:161], v[112:127]
	v_mfma_f32_32x32x16_bf16 v[96:111], v[138:141], v[162:165], v[96:111]
	v_mfma_f32_32x32x16_bf16 v[80:95], v[142:145], v[158:161], v[80:95]
	v_mfma_f32_32x32x16_bf16 v[64:79], v[142:145], v[162:165], v[64:79]
	v_mfma_f32_32x32x16_bf16 v[48:63], v[150:153], v[158:161], v[48:63]
	v_mfma_f32_32x32x16_bf16 v[32:47], v[150:153], v[162:165], v[32:47]
	s_setprio 0
	s_nor_b64 s[4:5], vcc, s[0:1]
	s_and_saveexec_b64 s[0:1], s[4:5]
	s_cbranch_execz .LBB0_224
	v_add_u32_e32 v132, v173, v146
	v_add_u32_e32 v138, v146, v176
	v_add_u32_e32 v140, v175, v146
	v_add_u32_e32 v142, v174, v146
	v_ashrrev_i32_e32 v133, 31, v132
	v_ashrrev_i32_e32 v139, 31, v138
	v_ashrrev_i32_e32 v141, 31, v140
	v_ashrrev_i32_e32 v143, 31, v142
	v_xor_b32_e32 v131, 0x10000, v131
	v_lshlrev_b64 v[132:133], 13, v[132:133]
	v_lshlrev_b64 v[138:139], 13, v[138:139]
	v_lshlrev_b64 v[140:141], 13, v[140:141]
	v_lshlrev_b64 v[142:143], 13, v[142:143]
	v_add_u32_e32 v131, 0, v131
	v_lshl_add_u64 v[132:133], v[136:137], 0, v[132:133]
	v_lshl_add_u64 v[138:139], v[136:137], 0, v[138:139]
	v_lshl_add_u64 v[140:141], v[136:137], 0, v[140:141]
	v_lshl_add_u64 v[136:137], v[136:137], 0, v[142:143]
	v_add_u32_e32 v142, v131, v180
	s_nop 0
	v_readfirstlane_b32 s4, v142
	s_mov_b32 m0, s4
	s_nop 0
	global_load_lds_dwordx4 v[138:139], off
	v_add_u32_e32 v138, v131, v179
	v_add_u32_e32 v139, v131, v178
	v_readfirstlane_b32 s4, v138
	s_mov_b32 m0, s4
	v_readfirstlane_b32 s4, v139
	v_add_u32_e32 v131, v131, v177
	global_load_lds_dwordx4 v[140:141], off
	s_mov_b32 m0, s4
	v_readfirstlane_b32 s4, v131
	global_load_lds_dwordx4 v[136:137], off
	s_mov_b32 m0, s4
	v_add_u32_e32 v136, 0x8000, v142
	global_load_lds_dwordx4 v[132:133], off
	v_add_u32_e32 v132, v148, v176
	v_ashrrev_i32_e32 v133, 31, v132
	v_lshlrev_b64 v[132:133], 13, v[132:133]
	v_readfirstlane_b32 s4, v136
	v_lshl_add_u64 v[132:133], v[134:135], 0, v[132:133]
	s_mov_b32 m0, s4
	v_add_u32_e32 v136, 0x8000, v138
	global_load_lds_dwordx4 v[132:133], off
	v_add_u32_e32 v132, v175, v148
	v_ashrrev_i32_e32 v133, 31, v132
	v_lshlrev_b64 v[132:133], 13, v[132:133]
	v_readfirstlane_b32 s4, v136
	v_lshl_add_u64 v[132:133], v[134:135], 0, v[132:133]
	s_mov_b32 m0, s4
	v_add_u32_e32 v136, 0x8000, v139
	global_load_lds_dwordx4 v[132:133], off
	v_add_u32_e32 v132, v174, v148
	v_ashrrev_i32_e32 v133, 31, v132
	v_lshlrev_b64 v[132:133], 13, v[132:133]
	v_readfirstlane_b32 s4, v136
	v_lshl_add_u64 v[132:133], v[134:135], 0, v[132:133]
	s_mov_b32 m0, s4
	v_add_u32_e32 v131, 0x8000, v131
	global_load_lds_dwordx4 v[132:133], off
	v_add_u32_e32 v132, v173, v148
	v_ashrrev_i32_e32 v133, 31, v132
	v_lshlrev_b64 v[132:133], 13, v[132:133]
	v_readfirstlane_b32 s4, v131
	v_lshl_add_u64 v[132:133], v[134:135], 0, v[132:133]
	s_mov_b32 m0, s4
	s_nop 0
	global_load_lds_dwordx4 v[132:133], off
	s_branch .LBB0_224
